# attention row max fused into v_max_f32_dpp (no self-max), rwkv light-prep LDS reads issued at chunk-loop top
# baseline (speedup 1.0000x reference)
; __device__ __forceinline__ bf16_t f2bf(float f) { return (bf16_t)(pack2(f, 0.f) & 0xffffu); }
; __device__ __forceinline__ void attn_tile(const Params& p, int l, int tile, unsigned char* smem) {
;     ...
;         float mx = fmaxf(fmaxf(sv0, sv1), fmaxf(sv2, sv3));
;         mx = max16(mx);
;         const float mn = fmaxf(m[mt][j], mx);
;         const float alpha = __expf(m[mt][j] - mn);
;         const float p0 = __expf(sv0 - mn), p1 = __expf(sv1 - mn), p2 = __expf(sv2 - mn), p3 = __expf(sv3 - mn);
;         bf16_t* pr = Ps + (mt * 16 + fq * 4 + j) * 72 + fr;
;         pr[0] = f2bf(p0); pr[16] = f2bf(p1); pr[32] = f2bf(p2); pr[48] = f2bf(p3);
;         const float rsum = sum16(p0 + p1 + p2 + p3);
;         ls[mt][j] = ls[mt][j] * alpha + rsum;
;         m[mt][j] = mn;
.LBB0_529:
	v_max_f32_e32 v125, v88, v92
	v_max3_f32 v125, v80, v84, v125
	v_add_u32_e32 v137, 49, v111
	s_andn2_b64 vcc, exec, s[48:49]
	v_max_f32_dpp v125, v125, v125 quad_perm:[1,0,3,2] row_mask:0xf bank_mask:0xf bound_ctrl:1
	v_cmp_lt_u32_e64 s[46:47], s89, v137
	s_nop 0
	v_max_f32_dpp v125, v125, v125 quad_perm:[2,3,0,1] row_mask:0xf bank_mask:0xf bound_ctrl:1
	s_nop 1
	v_max_f32_dpp v125, v125, v125 row_half_mirror row_mask:0xf bank_mask:0xf bound_ctrl:1
	s_nop 1
	v_mov_b32_dpp v136, v125 row_mirror row_mask:0xf bank_mask:0xf bound_ctrl:1
	v_max3_f32 v125, v129, v125, v136
	v_sub_f32_e32 v80, v80, v125
	v_sub_f32_e32 v84, v84, v125
	v_mul_f32_e32 v80, 0x3fb8aa3b, v80
	v_mul_f32_e32 v84, 0x3fb8aa3b, v84
	v_sub_f32_e32 v88, v88, v125
	v_exp_f32_e32 v80, v80
	v_exp_f32_e32 v84, v84
	v_mul_f32_e32 v88, 0x3fb8aa3b, v88
	v_sub_f32_e32 v92, v92, v125
	v_exp_f32_e32 v88, v88
	v_mul_f32_e32 v92, 0x3fb8aa3b, v92
	v_exp_f32_e32 v92, v92
	v_cvt_pk_bf16_f32 v136, v80, s0
	v_add_f32_e32 v80, v80, v84
	v_add_f32_e32 v80, v88, v80
	ds_write_b16 v115, v136 offset:18432
	v_cvt_pk_bf16_f32 v136, v84, s0
	v_add_f32_e32 v80, v92, v80
	ds_write_b16 v115, v136 offset:18464
	v_cvt_pk_bf16_f32 v136, v88, s0
	v_add_f32_dpp v80, v80, v80 quad_perm:[1,0,3,2] row_mask:0xf bank_mask:0xf bound_ctrl:1
	ds_write_b16 v115, v136 offset:18496
	v_cvt_pk_bf16_f32 v136, v92, s0
	v_add_f32_dpp v80, v80, v80 quad_perm:[2,3,0,1] row_mask:0xf bank_mask:0xf bound_ctrl:1
	ds_write_b16 v115, v136 offset:18528
	v_add_u32_e32 v136, 33, v111
	v_add_f32_dpp v84, v80, v80 row_half_mirror row_mask:0xf bank_mask:0xf bound_ctrl:1
	v_cndmask_b32_e64 v80, 0, 1, s[48:49]
	v_add_u32_e32 v92, 17, v111
	v_mov_b32_dpp v88, v84 row_mirror row_mask:0xf bank_mask:0xf bound_ctrl:1
	v_cmp_ne_u32_e64 s[44:45], 1, v80
	v_cmp_lt_u32_e64 s[48:49], s89, v136
	v_cmp_lt_u32_e64 s[50:51], s89, v92
	s_cbranch_vccnz .LBB0_531
	v_add_u32_e32 v80, 1, v111
	v_cmp_lt_u32_e32 vcc, s89, v80
	v_cndmask_b32_e64 v81, v205, v81, s[46:47]
	v_cndmask_b32_e64 v85, v205, v85, s[48:49]
	v_cndmask_b32_e64 v89, v205, v89, s[50:51]
	v_cndmask_b32_e32 v93, v205, v93, vcc
.LBB0_531:
	v_max_f32_e32 v80, v89, v93
	v_max3_f32 v80, v81, v85, v80
	v_add_u32_e32 v139, 50, v111
	s_and_b64 vcc, exec, s[44:45]
	v_max_f32_dpp v80, v80, v80 quad_perm:[1,0,3,2] row_mask:0xf bank_mask:0xf bound_ctrl:1
	v_cmp_lt_u32_e64 s[46:47], s89, v139
	s_nop 0
	v_max_f32_dpp v80, v80, v80 quad_perm:[2,3,0,1] row_mask:0xf bank_mask:0xf bound_ctrl:1
	s_nop 1
	v_max_f32_dpp v80, v80, v80 row_half_mirror row_mask:0xf bank_mask:0xf bound_ctrl:1
	s_nop 1
	v_mov_b32_dpp v138, v80 row_mirror row_mask:0xf bank_mask:0xf bound_ctrl:1
	v_max3_f32 v80, v128, v80, v138
	v_sub_f32_e32 v81, v81, v80
	v_sub_f32_e32 v85, v85, v80
	v_mul_f32_e32 v81, 0x3fb8aa3b, v81
	v_mul_f32_e32 v85, 0x3fb8aa3b, v85
	v_sub_f32_e32 v89, v89, v80
	v_exp_f32_e32 v81, v81
	v_exp_f32_e32 v85, v85
	v_mul_f32_e32 v89, 0x3fb8aa3b, v89
	v_sub_f32_e32 v93, v93, v80
	v_exp_f32_e32 v89, v89
	v_mul_f32_e32 v93, 0x3fb8aa3b, v93
	v_exp_f32_e32 v93, v93
	v_cvt_pk_bf16_f32 v138, v81, s0
	v_add_f32_e32 v81, v81, v85
	v_add_f32_e32 v81, v89, v81
	ds_write_b16 v115, v138 offset:18576
	v_cvt_pk_bf16_f32 v138, v85, s0
	v_add_f32_e32 v81, v93, v81
	ds_write_b16 v115, v138 offset:18608
	v_cvt_pk_bf16_f32 v138, v89, s0
	v_add_f32_dpp v81, v81, v81 quad_perm:[1,0,3,2] row_mask:0xf bank_mask:0xf bound_ctrl:1
	ds_write_b16 v115, v138 offset:18640
	v_cvt_pk_bf16_f32 v138, v93, s0
	v_add_f32_dpp v81, v81, v81 quad_perm:[2,3,0,1] row_mask:0xf bank_mask:0xf bound_ctrl:1
	ds_write_b16 v115, v138 offset:18672
	v_add_u32_e32 v138, 34, v111
	v_add_f32_dpp v85, v81, v81 row_half_mirror row_mask:0xf bank_mask:0xf bound_ctrl:1
	v_add_u32_e32 v93, 18, v111
	v_cmp_lt_u32_e64 s[48:49], s89, v138
	v_mov_b32_dpp v89, v85 row_mirror row_mask:0xf bank_mask:0xf bound_ctrl:1
	v_cmp_lt_u32_e64 s[50:51], s89, v93
	s_cbranch_vccnz .LBB0_533
	v_add_u32_e32 v81, 2, v111
	v_cmp_lt_u32_e32 vcc, s89, v81
	v_cndmask_b32_e64 v82, v205, v82, s[46:47]
	v_cndmask_b32_e64 v86, v205, v86, s[48:49]
	v_cndmask_b32_e64 v90, v205, v90, s[50:51]
	v_cndmask_b32_e32 v94, v205, v94, vcc
.LBB0_533:
	v_max_f32_e32 v81, v90, v94
	v_max3_f32 v81, v82, v86, v81
	v_add_u32_e32 v141, 51, v111
	s_and_b64 vcc, exec, s[44:45]
	v_max_f32_dpp v81, v81, v81 quad_perm:[1,0,3,2] row_mask:0xf bank_mask:0xf bound_ctrl:1
	v_cmp_lt_u32_e64 s[46:47], s89, v141
	s_nop 0
	v_max_f32_dpp v81, v81, v81 quad_perm:[2,3,0,1] row_mask:0xf bank_mask:0xf bound_ctrl:1
	s_nop 1
	v_max_f32_dpp v81, v81, v81 row_half_mirror row_mask:0xf bank_mask:0xf bound_ctrl:1
	s_nop 1
	v_mov_b32_dpp v140, v81 row_mirror row_mask:0xf bank_mask:0xf bound_ctrl:1
	v_max3_f32 v81, v127, v81, v140
	v_sub_f32_e32 v82, v82, v81
	v_sub_f32_e32 v86, v86, v81
	v_mul_f32_e32 v82, 0x3fb8aa3b, v82
	v_mul_f32_e32 v86, 0x3fb8aa3b, v86
	v_sub_f32_e32 v90, v90, v81
	v_exp_f32_e32 v82, v82
	v_exp_f32_e32 v86, v86
	v_mul_f32_e32 v90, 0x3fb8aa3b, v90
	v_sub_f32_e32 v94, v94, v81
	v_exp_f32_e32 v90, v90
	v_mul_f32_e32 v94, 0x3fb8aa3b, v94
	v_exp_f32_e32 v94, v94
	v_cvt_pk_bf16_f32 v140, v82, s0
	v_add_f32_e32 v82, v82, v86
	v_add_f32_e32 v82, v90, v82
	ds_write_b16 v115, v140 offset:18720
	v_cvt_pk_bf16_f32 v140, v86, s0
	v_add_f32_e32 v82, v94, v82
	ds_write_b16 v115, v140 offset:18752
	v_cvt_pk_bf16_f32 v140, v90, s0
	v_add_f32_dpp v82, v82, v82 quad_perm:[1,0,3,2] row_mask:0xf bank_mask:0xf bound_ctrl:1
	ds_write_b16 v115, v140 offset:18784
	v_cvt_pk_bf16_f32 v140, v94, s0
	v_add_f32_dpp v82, v82, v82 quad_perm:[2,3,0,1] row_mask:0xf bank_mask:0xf bound_ctrl:1
	ds_write_b16 v115, v140 offset:18816
	v_add_u32_e32 v140, 35, v111
	v_add_f32_dpp v86, v82, v82 row_half_mirror row_mask:0xf bank_mask:0xf bound_ctrl:1
	v_add_u32_e32 v94, 19, v111
	v_cmp_lt_u32_e64 s[48:49], s89, v140
	v_mov_b32_dpp v90, v86 row_mirror row_mask:0xf bank_mask:0xf bound_ctrl:1
	v_cmp_lt_u32_e64 s[50:51], s89, v94
	s_cbranch_vccnz .LBB0_535
	v_add_u32_e32 v82, 3, v111
	v_cmp_lt_u32_e32 vcc, s89, v82
	v_cndmask_b32_e64 v83, v205, v83, s[46:47]
	v_cndmask_b32_e64 v87, v205, v87, s[48:49]
	v_cndmask_b32_e64 v91, v205, v91, s[50:51]
	v_cndmask_b32_e32 v95, v205, v95, vcc
; __device__ __forceinline__ bf16_t f2bf(float f) { return (bf16_t)(pack2(f, 0.f) & 0xffffu); }
; __device__ __forceinline__ void attn_tile(const Params& p, int l, int tile, unsigned char* smem) {
;     ...
;         float mx = fmaxf(fmaxf(sv0, sv1), fmaxf(sv2, sv3));
;         mx = max16(mx);
;         const float mn = fmaxf(m[mt][j], mx);
;         const float alpha = __expf(m[mt][j] - mn);
;         const float p0 = __expf(sv0 - mn), p1 = __expf(sv1 - mn), p2 = __expf(sv2 - mn), p3 = __expf(sv3 - mn);
;         bf16_t* pr = Ps + (mt * 16 + fq * 4 + j) * 72 + fr;
;         pr[0] = f2bf(p0); pr[16] = f2bf(p1); pr[32] = f2bf(p2); pr[48] = f2bf(p3);
;         const float rsum = sum16(p0 + p1 + p2 + p3);
;         ls[mt][j] = ls[mt][j] * alpha + rsum;
;         m[mt][j] = mn;
.LBB0_535:
	v_max_f32_e32 v82, v91, v95
	v_max3_f32 v82, v83, v87, v82
	s_and_b64 vcc, exec, s[44:45]
	s_nop 0
	v_max_f32_dpp v82, v82, v82 quad_perm:[1,0,3,2] row_mask:0xf bank_mask:0xf bound_ctrl:1
	s_nop 1
	v_max_f32_dpp v82, v82, v82 quad_perm:[2,3,0,1] row_mask:0xf bank_mask:0xf bound_ctrl:1
	s_nop 1
	v_max_f32_dpp v82, v82, v82 row_half_mirror row_mask:0xf bank_mask:0xf bound_ctrl:1
	s_nop 1
	v_mov_b32_dpp v142, v82 row_mirror row_mask:0xf bank_mask:0xf bound_ctrl:1
	v_max3_f32 v82, v126, v82, v142
	v_sub_f32_e32 v83, v83, v82
	v_sub_f32_e32 v87, v87, v82
	v_mul_f32_e32 v83, 0x3fb8aa3b, v83
	v_mul_f32_e32 v87, 0x3fb8aa3b, v87
	v_sub_f32_e32 v91, v91, v82
	v_exp_f32_e32 v83, v83
	v_exp_f32_e32 v87, v87
	v_mul_f32_e32 v91, 0x3fb8aa3b, v91
	v_sub_f32_e32 v95, v95, v82
	v_exp_f32_e32 v91, v91
	v_mul_f32_e32 v95, 0x3fb8aa3b, v95
	v_exp_f32_e32 v95, v95
	v_cvt_pk_bf16_f32 v142, v83, s0
	v_add_f32_e32 v83, v83, v87
	v_add_f32_e32 v83, v91, v83
	v_add_f32_e32 v83, v95, v83
	ds_write_b16 v115, v142 offset:18864
	v_cvt_pk_bf16_f32 v142, v87, s0
	v_add_f32_dpp v83, v83, v83 quad_perm:[1,0,3,2] row_mask:0xf bank_mask:0xf bound_ctrl:1
	ds_write_b16 v115, v142 offset:18896
	v_cvt_pk_bf16_f32 v142, v91, s0
	v_add_f32_dpp v83, v83, v83 quad_perm:[2,3,0,1] row_mask:0xf bank_mask:0xf bound_ctrl:1
	ds_write_b16 v115, v142 offset:18928
	v_cvt_pk_bf16_f32 v142, v95, s0
	v_add_f32_dpp v87, v83, v83 row_half_mirror row_mask:0xf bank_mask:0xf bound_ctrl:1
	ds_write_b16 v115, v142 offset:18960
	s_nop 0
	v_mov_b32_dpp v91, v87 row_mirror row_mask:0xf bank_mask:0xf bound_ctrl:1
	s_cbranch_vccnz .LBB0_537
	v_add_u32_e32 v83, 64, v111
	v_cmp_lt_u32_e32 vcc, s89, v83
	s_nop 1
	v_cndmask_b32_e32 v64, v205, v64, vcc
	v_cmp_lt_u32_e32 vcc, s89, v134
	s_nop 1
	v_cndmask_b32_e32 v68, v205, v68, vcc
	v_cmp_lt_u32_e32 vcc, s89, v133
	s_nop 1
	v_cndmask_b32_e32 v72, v205, v72, vcc
	v_cmp_lt_u32_e32 vcc, s89, v135
	s_nop 1
	v_cndmask_b32_e32 v76, v205, v76, vcc
.LBB0_537:
	v_max_f32_e32 v83, v72, v76
	v_max3_f32 v83, v64, v68, v83
	s_and_b64 vcc, exec, s[44:45]
	s_nop 0
	v_max_f32_dpp v83, v83, v83 quad_perm:[1,0,3,2] row_mask:0xf bank_mask:0xf bound_ctrl:1
	s_nop 1
	v_max_f32_dpp v83, v83, v83 quad_perm:[2,3,0,1] row_mask:0xf bank_mask:0xf bound_ctrl:1
	s_nop 1
	v_max_f32_dpp v83, v83, v83 row_half_mirror row_mask:0xf bank_mask:0xf bound_ctrl:1
	s_nop 1
	v_mov_b32_dpp v95, v83 row_mirror row_mask:0xf bank_mask:0xf bound_ctrl:1
	v_max3_f32 v83, v132, v83, v95
	v_sub_f32_e32 v64, v64, v83
	v_sub_f32_e32 v68, v68, v83
	v_mul_f32_e32 v64, 0x3fb8aa3b, v64
	v_mul_f32_e32 v68, 0x3fb8aa3b, v68
	v_sub_f32_e32 v72, v72, v83
	v_exp_f32_e32 v64, v64
	v_exp_f32_e32 v68, v68
	v_mul_f32_e32 v72, 0x3fb8aa3b, v72
	v_sub_f32_e32 v76, v76, v83
	v_exp_f32_e32 v72, v72
	v_mul_f32_e32 v76, 0x3fb8aa3b, v76
	v_exp_f32_e32 v76, v76
	v_cvt_pk_bf16_f32 v95, v64, s0
	v_add_f32_e32 v64, v64, v68
	v_add_f32_e32 v64, v72, v64
	v_add_f32_e32 v64, v76, v64
	ds_write_b16 v115, v95 offset:20736
	v_cvt_pk_bf16_f32 v95, v68, s0
	v_add_f32_dpp v64, v64, v64 quad_perm:[1,0,3,2] row_mask:0xf bank_mask:0xf bound_ctrl:1
	ds_write_b16 v115, v95 offset:20768
	v_cvt_pk_bf16_f32 v95, v72, s0
	v_add_f32_dpp v64, v64, v64 quad_perm:[2,3,0,1] row_mask:0xf bank_mask:0xf bound_ctrl:1
	ds_write_b16 v115, v95 offset:20800
	v_cvt_pk_bf16_f32 v95, v76, s0
	v_add_f32_dpp v68, v64, v64 row_half_mirror row_mask:0xf bank_mask:0xf bound_ctrl:1
	ds_write_b16 v115, v95 offset:20832
	s_nop 0
	v_mov_b32_dpp v76, v68 row_mirror row_mask:0xf bank_mask:0xf bound_ctrl:1
	s_cbranch_vccnz .LBB0_539
	v_add_u32_e32 v64, 0x41, v111
	v_cmp_lt_u32_e32 vcc, s89, v64
	s_nop 1
	v_cndmask_b32_e32 v65, v205, v65, vcc
	v_cmp_lt_u32_e32 vcc, s89, v137
	s_nop 1
	v_cndmask_b32_e32 v69, v205, v69, vcc
	v_cmp_lt_u32_e32 vcc, s89, v136
	s_nop 1
	v_cndmask_b32_e32 v73, v205, v73, vcc
	v_cmp_lt_u32_e32 vcc, s89, v92
	s_nop 1
	v_cndmask_b32_e32 v77, v205, v77, vcc
.LBB0_539:
	v_max_f32_e32 v64, v73, v77
	v_max3_f32 v64, v65, v69, v64
	s_and_b64 vcc, exec, s[44:45]
	s_nop 0
	v_max_f32_dpp v64, v64, v64 quad_perm:[1,0,3,2] row_mask:0xf bank_mask:0xf bound_ctrl:1
	s_nop 1
	v_max_f32_dpp v64, v64, v64 quad_perm:[2,3,0,1] row_mask:0xf bank_mask:0xf bound_ctrl:1
	s_nop 1
	v_max_f32_dpp v64, v64, v64 row_half_mirror row_mask:0xf bank_mask:0xf bound_ctrl:1
	s_nop 1
	v_mov_b32_dpp v72, v64 row_mirror row_mask:0xf bank_mask:0xf bound_ctrl:1
	v_max3_f32 v72, v131, v64, v72
	v_sub_f32_e32 v64, v65, v72
	v_sub_f32_e32 v65, v69, v72
	v_mul_f32_e32 v64, 0x3fb8aa3b, v64
	v_mul_f32_e32 v65, 0x3fb8aa3b, v65
	v_sub_f32_e32 v69, v73, v72
	v_exp_f32_e32 v64, v64
	v_exp_f32_e32 v65, v65
	v_mul_f32_e32 v69, 0x3fb8aa3b, v69
	v_sub_f32_e32 v73, v77, v72
	v_exp_f32_e32 v69, v69
	v_mul_f32_e32 v73, 0x3fb8aa3b, v73
	v_exp_f32_e32 v73, v73
	v_cvt_pk_bf16_f32 v77, v64, s0
	v_add_f32_e32 v64, v64, v65
	v_add_f32_e32 v64, v69, v64
	v_add_f32_e32 v64, v73, v64
	ds_write_b16 v115, v77 offset:20880
	v_cvt_pk_bf16_f32 v77, v65, s0
	v_add_f32_dpp v64, v64, v64 quad_perm:[1,0,3,2] row_mask:0xf bank_mask:0xf bound_ctrl:1
	ds_write_b16 v115, v77 offset:20912
	v_cvt_pk_bf16_f32 v77, v69, s0
	v_add_f32_dpp v64, v64, v64 quad_perm:[2,3,0,1] row_mask:0xf bank_mask:0xf bound_ctrl:1
	ds_write_b16 v115, v77 offset:20944
	v_cvt_pk_bf16_f32 v77, v73, s0
	v_add_f32_dpp v65, v64, v64 row_half_mirror row_mask:0xf bank_mask:0xf bound_ctrl:1
	ds_write_b16 v115, v77 offset:20976
	s_nop 0
	v_mov_b32_dpp v69, v65 row_mirror row_mask:0xf bank_mask:0xf bound_ctrl:1
	s_cbranch_vccnz .LBB0_541
	v_add_u32_e32 v64, 0x42, v111
	v_cmp_lt_u32_e32 vcc, s89, v64
	s_nop 1
	v_cndmask_b32_e32 v66, v205, v66, vcc
	v_cmp_lt_u32_e32 vcc, s89, v139
	s_nop 1
	v_cndmask_b32_e32 v70, v205, v70, vcc
	v_cmp_lt_u32_e32 vcc, s89, v138
	s_nop 1
	v_cndmask_b32_e32 v74, v205, v74, vcc
	v_cmp_lt_u32_e32 vcc, s89, v93
	s_nop 1
	v_cndmask_b32_e32 v78, v205, v78, vcc
; __device__ __forceinline__ bf16_t f2bf(float f) { return (bf16_t)(pack2(f, 0.f) & 0xffffu); }
; __device__ __forceinline__ void attn_tile(const Params& p, int l, int tile, unsigned char* smem) {
;     ...
;         float mx = fmaxf(fmaxf(sv0, sv1), fmaxf(sv2, sv3));
;         mx = max16(mx);
;         const float mn = fmaxf(m[mt][j], mx);
;         const float alpha = __expf(m[mt][j] - mn);
;         const float p0 = __expf(sv0 - mn), p1 = __expf(sv1 - mn), p2 = __expf(sv2 - mn), p3 = __expf(sv3 - mn);
;         bf16_t* pr = Ps + (mt * 16 + fq * 4 + j) * 72 + fr;
;         pr[0] = f2bf(p0); pr[16] = f2bf(p1); pr[32] = f2bf(p2); pr[48] = f2bf(p3);
;         const float rsum = sum16(p0 + p1 + p2 + p3);
.LBB0_541:
	v_max_f32_e32 v64, v74, v78
	v_max3_f32 v64, v66, v70, v64
	s_and_b64 vcc, exec, s[44:45]
	s_nop 0
	v_max_f32_dpp v64, v64, v64 quad_perm:[1,0,3,2] row_mask:0xf bank_mask:0xf bound_ctrl:1
	s_nop 1
	v_max_f32_dpp v64, v64, v64 quad_perm:[2,3,0,1] row_mask:0xf bank_mask:0xf bound_ctrl:1
	s_nop 1
	v_max_f32_dpp v64, v64, v64 row_half_mirror row_mask:0xf bank_mask:0xf bound_ctrl:1
	s_nop 1
	v_mov_b32_dpp v73, v64 row_mirror row_mask:0xf bank_mask:0xf bound_ctrl:1
	v_max3_f32 v73, v130, v64, v73
	v_sub_f32_e32 v64, v66, v73
	v_sub_f32_e32 v66, v70, v73
	v_mul_f32_e32 v64, 0x3fb8aa3b, v64
	v_mul_f32_e32 v66, 0x3fb8aa3b, v66
	v_sub_f32_e32 v70, v74, v73
	v_exp_f32_e32 v64, v64
	v_exp_f32_e32 v66, v66
	v_mul_f32_e32 v70, 0x3fb8aa3b, v70
	v_sub_f32_e32 v74, v78, v73
	v_exp_f32_e32 v70, v70
	v_mul_f32_e32 v74, 0x3fb8aa3b, v74
	v_exp_f32_e32 v74, v74
	v_cvt_pk_bf16_f32 v77, v64, s0
	v_add_f32_e32 v64, v64, v66
	v_add_f32_e32 v64, v70, v64
	v_add_f32_e32 v64, v74, v64
	ds_write_b16 v115, v77 offset:21024
	v_cvt_pk_bf16_f32 v77, v66, s0
	v_add_f32_dpp v64, v64, v64 quad_perm:[1,0,3,2] row_mask:0xf bank_mask:0xf bound_ctrl:1
	ds_write_b16 v115, v77 offset:21056
	v_cvt_pk_bf16_f32 v77, v70, s0
	v_add_f32_dpp v64, v64, v64 quad_perm:[2,3,0,1] row_mask:0xf bank_mask:0xf bound_ctrl:1
	ds_write_b16 v115, v77 offset:21088
	v_cvt_pk_bf16_f32 v77, v74, s0
	v_add_f32_dpp v64, v64, v64 row_half_mirror row_mask:0xf bank_mask:0xf bound_ctrl:1
	ds_write_b16 v115, v77 offset:21120
	s_nop 0
	v_mov_b32_dpp v66, v64 row_mirror row_mask:0xf bank_mask:0xf bound_ctrl:1
	s_cbranch_vccnz .LBB0_543
	v_add_u32_e32 v70, 0x43, v111
	v_cmp_lt_u32_e32 vcc, s89, v70
	s_nop 1
	v_cndmask_b32_e32 v67, v205, v67, vcc
	v_cmp_lt_u32_e32 vcc, s89, v141
	s_nop 1
	v_cndmask_b32_e32 v71, v205, v71, vcc
	v_cmp_lt_u32_e32 vcc, s89, v140
	s_nop 1
	v_cndmask_b32_e32 v75, v205, v75, vcc
	v_cmp_lt_u32_e32 vcc, s89, v94
	s_nop 1
	v_cndmask_b32_e32 v79, v205, v79, vcc
; __device__ __forceinline__ bf16_t f2bf(float f) { return (bf16_t)(pack2(f, 0.f) & 0xffffu); }
; #define MFMA(a, b, c) __builtin_amdgcn_mfma_f32_16x16x32_bf16(a, b, c, 0, 0, 0)
; __device__ __forceinline__ void attn_tile(const Params& p, int l, int tile, unsigned char* smem) {
;     ...
;         float mx = fmaxf(fmaxf(sv0, sv1), fmaxf(sv2, sv3));
;         mx = max16(mx);
;         const float mn = fmaxf(m[mt][j], mx);
;         const float alpha = __expf(m[mt][j] - mn);
;         const float p0 = __expf(sv0 - mn), p1 = __expf(sv1 - mn), p2 = __expf(sv2 - mn), p3 = __expf(sv3 - mn);
;         bf16_t* pr = Ps + (mt * 16 + fq * 4 + j) * 72 + fr;
;         pr[0] = f2bf(p0); pr[16] = f2bf(p1); pr[32] = f2bf(p2); pr[48] = f2bf(p3);
;         const float rsum = sum16(p0 + p1 + p2 + p3);
;         ls[mt][j] = ls[mt][j] * alpha + rsum;
;         m[mt][j] = mn;
; #pragma unroll
;         for (int nt = 0; nt < 4; ++nt) o[mt][nt][j] *= alpha;
;       }
;     }
;     __builtin_amdgcn_wave_barrier();
; #pragma unroll
;     for (int ks = 0; ks < 2; ++ks) {
;       bf16x8 pa[2];
; #pragma unroll
;       for (int mt = 0; mt < 2; ++mt) pa[mt] = *(const bf16x8*)(Ps + (mt * 16 + fr) * 72 + ks * 32 + fq * 8);
; #pragma unroll
;       for (int nt = 0; nt < 4; ++nt) {
;         bf16x8 vb = *(const bf16x8*)(Vt + (nt * 16 + fr) * 72 + ks * 32 + fq * 8);
; #pragma unroll
;         for (int mt = 0; mt < 2; ++mt) o[mt][nt] = MFMA(pa[mt], vb, o[mt][nt]);
;       }
;     }
.LBB0_543:
	v_sub_f32_e32 v74, v131, v72
	v_mul_f32_e32 v74, 0x3fb8aa3b, v74
	v_exp_f32_e32 v77, v74
	v_sub_f32_e32 v74, v130, v73
	v_mul_f32_e32 v74, 0x3fb8aa3b, v74
	v_exp_f32_e32 v78, v74
	v_max_f32_e32 v74, v75, v79
	v_max3_f32 v74, v67, v71, v74
	v_add_f32_e32 v64, v64, v66
	v_sub_f32_e32 v66, v129, v125
	v_max_f32_dpp v74, v74, v74 quad_perm:[1,0,3,2] row_mask:0xf bank_mask:0xf bound_ctrl:1
	v_mul_f32_e32 v66, 0x3fb8aa3b, v66
	v_exp_f32_e32 v142, v66
	v_max_f32_dpp v74, v74, v74 quad_perm:[2,3,0,1] row_mask:0xf bank_mask:0xf bound_ctrl:1
	v_sub_f32_e32 v66, v128, v80
	v_mul_f32_e32 v66, 0x3fb8aa3b, v66
	v_max_f32_dpp v74, v74, v74 row_half_mirror row_mask:0xf bank_mask:0xf bound_ctrl:1
	v_exp_f32_e32 v143, v66
	v_sub_f32_e32 v66, v127, v81
	v_mov_b32_dpp v92, v74 row_mirror row_mask:0xf bank_mask:0xf bound_ctrl:1
	v_max3_f32 v74, v117, v74, v92
	v_sub_f32_e32 v67, v67, v74
	v_mul_f32_e32 v67, 0x3fb8aa3b, v67
	v_exp_f32_e32 v145, v67
	v_sub_f32_e32 v67, v71, v74
	v_mul_f32_e32 v67, 0x3fb8aa3b, v67
	v_exp_f32_e32 v146, v67
	v_sub_f32_e32 v67, v75, v74
	v_mul_f32_e32 v67, 0x3fb8aa3b, v67
	v_exp_f32_e32 v75, v67
	v_sub_f32_e32 v67, v79, v74
	v_mul_f32_e32 v67, 0x3fb8aa3b, v67
	v_exp_f32_e32 v147, v67
	v_cvt_pk_bf16_f32 v67, v145, s0
	ds_write_b16 v115, v67 offset:21168
	v_cvt_pk_bf16_f32 v67, v146, s0
	ds_write_b16 v115, v67 offset:21200
	v_cvt_pk_bf16_f32 v67, v75, s0
	v_mul_f32_e32 v66, 0x3fb8aa3b, v66
	ds_write_b16 v115, v67 offset:21232
	v_cvt_pk_bf16_f32 v67, v147, s0
	v_exp_f32_e32 v144, v66
	v_sub_f32_e32 v66, v126, v82
	ds_write_b16 v115, v67 offset:21264
	ds_read_b128 v[92:95], v113 offset:18432
	v_mul_f32_e32 v66, 0x3fb8aa3b, v66
	v_sub_f32_e32 v70, v132, v83
	v_exp_f32_e32 v71, v66
	v_sub_f32_e32 v66, v117, v74
	v_mul_f32_e32 v70, 0x3fb8aa3b, v70
	v_mul_f32_e32 v66, 0x3fb8aa3b, v66
	v_exp_f32_e32 v70, v70
	ds_read_b128 v[126:129], v113 offset:20736
	ds_read_b128 v[130:133], v114 offset:9216
	v_exp_f32_e32 v117, v66
	v_mul_f32_e32 v13, v13, v77
	v_mul_f32_e32 v12, v12, v70
	v_mul_f32_e32 v14, v14, v78
	v_mul_f32_e32 v28, v28, v142
	v_mul_f32_e32 v29, v29, v143
	v_mul_f32_e32 v30, v30, v144
	v_mul_f32_e32 v31, v31, v71
	v_mul_f32_e32 v15, v15, v117
	ds_read_b128 v[134:137], v114 offset:11520
	s_waitcnt lgkmcnt(1)
	v_mfma_f32_16x16x32_bf16 v[28:31], v[92:95], v[130:133], v[28:31]
	v_mul_f32_e32 v8, v8, v70
	v_mul_f32_e32 v4, v4, v70
	v_mul_f32_e32 v9, v9, v77
	v_mfma_f32_16x16x32_bf16 v[12:15], v[126:129], v[130:133], v[12:15]
	ds_read_b128 v[130:133], v114 offset:13824
	v_mul_f32_e32 v5, v5, v77
	v_mul_f32_e32 v10, v10, v78
	v_mul_f32_e32 v6, v6, v78
	v_mul_f32_e32 v20, v20, v142
	v_mul_f32_e32 v16, v16, v142
	v_mul_f32_e32 v21, v21, v143
	v_mul_f32_e32 v22, v22, v144
	v_mul_f32_e32 v23, v23, v71
	v_mul_f32_e32 v11, v11, v117
	v_mul_f32_e32 v17, v17, v143
	v_mul_f32_e32 v18, v18, v144
	v_mul_f32_e32 v19, v19, v71
	v_mul_f32_e32 v7, v7, v117
	v_mul_f32_e32 v24, v24, v142
	s_waitcnt lgkmcnt(0)
	v_mfma_f32_16x16x32_bf16 v[16:19], v[92:95], v[130:133], v[16:19]
	v_mul_f32_e32 v25, v25, v143
	v_mul_f32_e32 v26, v26, v144
	v_mul_f32_e32 v27, v27, v71
	v_mfma_f32_16x16x32_bf16 v[4:7], v[126:129], v[130:133], v[4:7]
	ds_read_b128 v[130:133], v113 offset:18496
	v_add_f32_e32 v66, v65, v69
	v_mul_f32_e32 v1, v1, v77
	v_mfma_f32_16x16x32_bf16 v[20:23], v[92:95], v[134:137], v[20:23]
	v_mul_f32_e32 v2, v2, v78
	v_fmac_f32_e32 v64, v123, v78
	v_fmac_f32_e32 v66, v124, v77
	v_mfma_f32_16x16x32_bf16 v[8:11], v[126:129], v[134:137], v[8:11]
	ds_read_b128 v[134:137], v114 offset:16128
	v_add_f32_e32 v67, v68, v76
	v_add_f32_e32 v68, v87, v91
	s_waitcnt lgkmcnt(0)
	v_mfma_f32_16x16x32_bf16 v[24:27], v[92:95], v[134:137], v[24:27]
	ds_read_b128 v[92:95], v113 offset:20800
	ds_read_b128 v[138:141], v114 offset:9280
	ds_read_b128 v[76:79], v114 offset:11584
	v_add_f32_e32 v69, v86, v90
	v_mul_f32_e32 v0, v0, v70
	v_mul_f32_e32 v3, v3, v117
	v_fmac_f32_e32 v67, v122, v70
	v_fmac_f32_e32 v68, v121, v71
	v_fmac_f32_e32 v69, v120, v144
	ds_read_b128 v[120:123], v114 offset:13888
	s_waitcnt lgkmcnt(1)
	v_mfma_f32_16x16x32_bf16 v[20:23], v[130:133], v[76:79], v[20:23]
	v_add_f32_e32 v65, v145, v146
	v_add_f32_e32 v65, v75, v65
	v_add_f32_e32 v65, v147, v65
	v_mfma_f32_16x16x32_bf16 v[8:11], v[92:95], v[76:79], v[8:11]
	ds_read_b128 v[76:79], v114 offset:16192
	v_add_f32_dpp v65, v65, v65 quad_perm:[1,0,3,2] row_mask:0xf bank_mask:0xf bound_ctrl:1
	v_add_f32_e32 v70, v85, v89
	v_mfma_f32_16x16x32_bf16 v[0:3], v[126:129], v[134:137], v[0:3]
	v_add_f32_dpp v65, v65, v65 quad_perm:[2,3,0,1] row_mask:0xf bank_mask:0xf bound_ctrl:1
	v_add_f32_e32 v71, v84, v88
	s_add_i32 s67, s67, 1
	v_mfma_f32_16x16x32_bf16 v[28:31], v[130:133], v[138:141], v[28:31]
	v_add_f32_dpp v65, v65, v65 row_half_mirror row_mask:0xf bank_mask:0xf bound_ctrl:1
	s_add_i32 s68, s68, 64
	v_fmac_f32_e32 v70, v118, v143
	v_mfma_f32_16x16x32_bf16 v[12:15], v[92:95], v[138:141], v[12:15]
	v_add_f32_dpp v65, v65, v65 row_mirror row_mask:0xf bank_mask:0xf bound_ctrl:1
	v_fmac_f32_e32 v71, v119, v142
	v_fmac_f32_e32 v65, v116, v117
	s_waitcnt lgkmcnt(1)
	v_mfma_f32_16x16x32_bf16 v[16:19], v[130:133], v[120:123], v[16:19]
	s_cmp_lg_u32 s59, s67
	v_subrev_u32_e32 v111, 64, v111
	v_mfma_f32_16x16x32_bf16 v[4:7], v[92:95], v[120:123], v[4:7]
	s_waitcnt lgkmcnt(0)
	v_mfma_f32_16x16x32_bf16 v[24:27], v[130:133], v[76:79], v[24:27]
	v_mfma_f32_16x16x32_bf16 v[0:3], v[92:95], v[76:79], v[0:3]
	s_cbranch_scc0 .LBB0_505
	v_mov_b32_e32 v117, v74
	v_mov_b32_e32 v130, v73
	v_mov_b32_e32 v131, v72
	v_mov_b32_e32 v132, v83
	v_mov_b32_e32 v126, v82
	v_mov_b32_e32 v127, v81
	v_mov_b32_e32 v128, v80
	v_mov_b32_e32 v129, v125
	v_mov_b32_e32 v116, v65
	v_mov_b32_e32 v123, v64
	v_mov_b32_e32 v124, v66
	v_mov_b32_e32 v122, v67
	v_mov_b32_e32 v121, v68
	v_mov_b32_e32 v120, v69
	v_mov_b32_e32 v118, v70
	v_mov_b32_e32 v119, v71
	s_branch .LBB0_525
